# prep forward-substitution block: LDS read-modify-writes and T-inverse operand reads batched behind single waits; attention unit end no longer drains its output stores before the workgroup barrier
# baseline (speedup 1.0000x reference)
; __device__ __forceinline__ unsigned cvt_pk_bf16(float lo, float hi) { const bf16v2_t r = __builtin_convertvector((f32v2_t){lo, hi}, bf16v2_t); return __builtin_bit_cast(unsigned, r); }
; template <int M> __device__ __forceinline__ float swz(float v) { return __int_as_float(__builtin_amdgcn_ds_swizzle(__float_as_int(v), (M << 10) | 0x1F)); }
; __device__ __forceinline__ int crow(int r, int hi) { return (r & 3) + 8 * (r >> 2) + 4 * hi; }
; __device__ __forceinline__ void attn_unit(LAS unsigned char* lds, const bf16_t* __restrict__ Q, const bf16_t* __restrict__ Kg, const bf16_t* __restrict__ Vg, bf16_t* __restrict__ AO, int b, int h, int qb) {
;     ...
;     for (int r = 0; r < 16; ++r) { const int orow = crow(r, hi); const float rl = __builtin_amdgcn_rcpf(li_l[orow]);
; #pragma unroll
;         for (int d0 = 0; d0 < 4; ++d0) { const float v = o[d0][r] * rl; const float vn = swz<1>(v);
;             if ((r32 & 1) == 0) *(unsigned*)(Ow + (size_t)orow * 1024 + d0 * 32 + r32) = cvt_pk_bf16(v, vn); } }
;     __syncthreads();
; __global__ void __launch_bounds__(NTHR) mega(Params p) {
;     ...
;                 for (;;) { if (threadIdx.x == 0) misc[0] = (int)atomicAdd(ctr + l + 2 * rp, 1u);
;                     __syncthreads(); const int i = misc[0]; __syncthreads();
;                     if (i >= 512) break;
;                     att::attn_unit(lds, (const bf16_t*)(ws + AR_Q), (const bf16_t*)(ws + AR_K), (const bf16_t*)(ws + AR_V), (bf16_t*)(ws + AR_AO), (i & 63) >> 3, i & 7, 7 - (i >> 6)); }
.LBB0_292:
	v_readlane_b32 s0, v255, 32
	v_readlane_b32 s1, v255, 33
	v_readlane_b32 s36, v252, 0
	s_lshl_b64 s[0:1], s[0:1], 2
	v_readlane_b32 s50, v252, 14
	v_readlane_b32 s51, v252, 15
	s_add_u32 s90, s50, s0
	s_addc_u32 s91, s51, s1
	v_readlane_b32 s37, v252, 1
	v_readlane_b32 s38, v252, 2
	v_readlane_b32 s39, v252, 3
	v_readlane_b32 s40, v252, 4
	v_readlane_b32 s41, v252, 5
	v_readlane_b32 s42, v252, 6
	v_readlane_b32 s43, v252, 7
	v_readlane_b32 s44, v252, 8
	v_readlane_b32 s45, v252, 9
	v_readlane_b32 s46, v252, 10
	v_readlane_b32 s47, v252, 11
	v_readlane_b32 s48, v252, 12
	v_readlane_b32 s49, v252, 13
	s_branch .LBB0_295
.LBB0_293:
	s_or_b64 exec, exec, s[0:1]
	s_mov_b64 s[0:1], 0
	s_waitcnt lgkmcnt(0)
	s_barrier
.LBB0_294:
	s_and_b64 vcc, exec, s[0:1]
	s_cbranch_vccnz .LBB0_483

; #define LAS __attribute__((address_space(3)))
; __device__ __forceinline__ void prep_unit(LAS unsigned char* lds, const Params& p, int l, int unit) {
;     ...
;           for (int r = 0; r < 4; ++r) { LAS float* x0 = Xb0 + (16 * I + 4 * lq + r) * XS + li; LAS float* x1 = Xb1 + (16 * I + 4 * lq + r) * XS + li; *x0 -= a0[r]; *x1 -= a1[r]; }
;           asm volatile("s_waitcnt lgkmcnt(0)" ::: "memory");
;           f32x4 y0 = {0.f, 0.f, 0.f, 0.f}, y1 = {0.f, 0.f, 0.f, 0.f};
;           const LAS float* pt = TI + (I * 16 + li) * 16 + lq;
; #pragma unroll
;           for (int sx = 0; sx < 4; ++sx) { const float tvv = pt[4 * sx];
;               y0 = __builtin_amdgcn_mfma_f32_16x16x4f32(tvv, Xb0[(16 * I + 4 * sx + lq) * XS + li], y0, 0, 0, 0);
;               y1 = __builtin_amdgcn_mfma_f32_16x16x4f32(tvv, Xb1[(16 * I + 4 * sx + lq) * XS + li], y1, 0, 0, 0); }
; #pragma unroll
;           for (int r = 0; r < 4; ++r) { Xb0[(16 * I + 4 * lq + r) * XS + li] = y0[r]; Xb1[(16 * I + 4 * lq + r) * XS + li] = y1[r]; }
.LBB0_654:
	v_or_b32_e32 v32, s1, v20
	s_movk_i32 s3, 0x84
	v_mul_lo_u32 v34, v32, s3
	v_lshlrev_b32_e32 v32, 2, v34
	v_add_u32_e32 v35, v26, v32
	v_add_u32_e32 v32, v27, v32
	ds_read_b32 v136, v35
	ds_read_b32 v137, v32
	ds_read_b32 v138, v35 offset:528
	ds_read_b32 v139, v32 offset:528
	ds_read_b32 v140, v35 offset:1056
	ds_read_b32 v141, v32 offset:1056
	ds_read_b32 v142, v35 offset:1584
	ds_read_b32 v143, v32 offset:1584
	s_add_i32 s0, s0, 1
	s_cmp_eq_u32 s0, 4
	v_add_u32_e32 v31, 0x1000, v31
	v_or_b32_e32 v156, s1, v18
	v_lshl_add_u32 v36, v156, 6, v28
	s_waitcnt lgkmcnt(0)
	v_sub_f32_e32 v136, v136, v4
	v_sub_f32_e32 v137, v137, v0
	v_sub_f32_e32 v138, v138, v5
	v_sub_f32_e32 v139, v139, v1
	v_sub_f32_e32 v140, v140, v6
	v_sub_f32_e32 v141, v141, v2
	v_sub_f32_e32 v142, v142, v7
	v_sub_f32_e32 v143, v143, v3
	ds_write_b32 v35, v136
	ds_write_b32 v32, v137
	ds_write_b32 v35, v138 offset:528
	ds_write_b32 v32, v139 offset:528
	ds_write_b32 v35, v140 offset:1056
	ds_write_b32 v32, v141 offset:1056
	ds_write_b32 v35, v142 offset:1584
	ds_write_b32 v32, v143 offset:1584
	s_waitcnt lgkmcnt(0)
	ds_read2_b32 v[144:145], v36 offset1:4
	ds_read2_b32 v[146:147], v36 offset0:8 offset1:12
	v_or_b32_e32 v0, s1, v19
	v_mul_lo_u32 v4, v0, s3
	v_lshl_add_u32 v37, v4, 2, v26
	v_add_u32_e32 v4, v4, v18
	v_lshl_add_u32 v38, v4, 2, v22
	ds_read_b32 v148, v37
	ds_read_b32 v149, v38
	ds_read_b32 v150, v37 offset:2112
	ds_read_b32 v151, v38 offset:2112
	ds_read_b32 v152, v37 offset:4224
	ds_read_b32 v153, v38 offset:4224
	ds_read_b32 v154, v37 offset:6336
	ds_read_b32 v155, v38 offset:6336
	v_or_b32_e32 v32, v34, v18
	v_lshlrev_b32_e32 v32, 2, v32
	v_add_u32_e32 v34, v34, v18
	v_add_u32_e32 v37, v21, v32
	v_lshl_add_u32 v34, v34, 2, v22
	v_add_u32_e32 v32, v22, v32
	s_waitcnt lgkmcnt(0)
	v_mfma_f32_16x16x4_f32 v[0:3], v144, v148, 0
	v_mfma_f32_16x16x4_f32 v[4:7], v144, v149, 0
	v_mfma_f32_16x16x4_f32 v[0:3], v145, v150, v[0:3]
	v_mfma_f32_16x16x4_f32 v[4:7], v145, v151, v[4:7]
	v_mfma_f32_16x16x4_f32 v[0:3], v146, v152, v[0:3]
	v_mfma_f32_16x16x4_f32 v[4:7], v146, v153, v[4:7]
	v_mfma_f32_16x16x4_f32 v[0:3], v147, v154, v[0:3]
	v_mfma_f32_16x16x4_f32 v[4:7], v147, v155, v[4:7]
	s_nop 9
	ds_write_b32 v37, v0
	ds_write_b32 v32, v4
	ds_write_b32 v35, v1 offset:528
	ds_write_b32 v34, v5 offset:528
	ds_write_b32 v35, v2 offset:1056
	ds_write_b32 v34, v6 offset:1056
	ds_write_b32 v35, v3 offset:1584
	ds_write_b32 v34, v7 offset:1584
	s_waitcnt lgkmcnt(0)
	s_cbranch_scc1 .LBB0_599
